# in-proj phase: workgroups with two GEMM tiles (bid >= 96) convert this layer's FFN weights before their tiles instead of after
# baseline (speedup 1.0000x reference)
; __device__ __forceinline__ void convert_layer(const Params& p, const Lt& lt, int l, int glo, int ghi, int c, int nc, float* tile) {
;     unsigned char* ws = p.ws;
; #pragma unroll 1
;     for (int m = 0; m < 4; ++m) {
;         const int off = m == 0 ? 0 : (m == 1 ? 608 : (m == 2 ? 864 : 1888)), n = m == 0 ? 608 : (m == 1 ? 256 : 1024);
;         const int lo = (glo > off ? glo : off) - off, hi = (ghi < off + n ? ghi : off + n) - off;
;         if (lo >= hi) continue;
;         const float* src = m == 0 ? p.in[2] + (size_t)l * DM * INC : (m == 1 ? p.in[21] + (size_t)l * DM * DM : (m == 2 ? p.in[23] + (size_t)l * DM * DFF : p.in[24] + (size_t)l * DFF * DM));
;         bf16_t* dst = (bf16_t*)(m == 0 ? ws + WS_WIN + l * SZ_WIN : (m == 1 ? ws + WS_WOUT + l * SZ_WOUT : (m == 2 ? ws + WS_WUP + l * SZ_WUP : ws + WS_WDN + l * SZ_WDN)));
;         const float* scale = m == 0 ? p.in[1] + l * DM : (m == 2 ? p.in[22] + l * DM : nullptr);
;         const int K = m == 3 ? DFF : DM, N = m == 0 ? INC : (m == 2 ? DFF : DM);
;         transpose_big(lt, src, dst, scale, K, N, lo, hi, off - glo, c, nc, tile);
;     }
; }
.Lconv_return:
	s_cmp_eq_u32 s38, 0
	s_cbranch_scc1 .Lconv_ret0
	s_cmp_eq_u32 s38, 1
	s_cbranch_scc1 .LBB0_464
	s_cmp_eq_u32 s38, 2
	s_cbranch_scc1 .LBB0_259
	s_cmp_eq_u32 s38, 5
	s_cbranch_scc1 .Lconv_ret5
	s_branch .LBB0_337

; #define LAS __attribute__((address_space(3)))
;     __device__ bool next(int i, Unit& u) const {
;         const long L = (long)i * G + c; if (L >= nwg) return false;
;         int wgid = (int)L; { const int q = nwg / NXCD, r = nwg % NXCD, xcd = wgid % NXCD, off = wgid / NXCD; wgid = (xcd < r ? xcd * (q + 1) : r * (q + 1) + (xcd - r) * q) + off; }
;         const int nig = WGM * nN, gid = wgid / nig, fm = gid * WGM, gsz = (nM - fm) < WGM ? (nM - fm) : WGM;
;         u.pm = fm + ((wgid % nig) % gsz); u.pn = (wgid % nig) / gsz; return true;
;     }
; template <bool COOP>
; __global__ void __launch_bounds__(NTHREADS, 2) mega(Params p0) {
;     ...
;                 pg8::Gemm g{(const bf16_t*)(ws + WS_XB), (const bf16_t*)(ws + WS_WIN + l * SZ_WIN), SEQ, INC, DM}; pg8::StaticOrder S; S.init(SEQ, INC, G, lt.bid);
;                 EpiScaleBf16<0> E{(bf16_t*)(ws + WS_P), INC, (const float*)(ws + WS_SSQ)};
;                 pg8::gemm_phase(lt, (LAS unsigned char*)lds, g, S, E);
;                 if (G == 256 && lt.bid >= 96 && !(ph0 & 1)) { __syncthreads(); convert_layer(p, lt, l, 864, CONV_TILES, lt.bid - 96, 160, (float*)lds); } }
.LBB0_392:
	s_and_b64 vcc, exec, s[6:7]
	s_cbranch_vccz .LBB0_464
	s_cmpk_lt_u32 s86, 0x60
	s_cbranch_scc1 .Lconv_ret5
	v_readlane_b32 s37, v254, 1
	s_add_i32 s34, s86, 0x300
	s_movk_i32 s35, 0xb60
	s_movk_i32 s36, 0xa0
	s_mov_b32 s38, 5
	s_branch .Lconv_entry
.Lconv_ret5:
	s_cmpk_lt_i32 s86, 0x260
	s_cselect_b64 s[0:1], -1, 0
	s_cmpk_gt_i32 s86, 0x25f
	v_readfirstlane_b32 s10, v245
	s_cbranch_scc1 .LBB0_395
	s_ashr_i32 s4, s86, 31
	s_lshr_b32 s4, s4, 29
	s_add_i32 s4, s86, s4
	s_ashr_i32 s5, s4, 3
	s_and_b32 s4, s4, -8
	s_sub_i32 s4, s86, s4
	s_cmp_lt_i32 s4, 0
	s_movk_i32 s6, 0x4d
	s_cselect_b32 s6, s6, 0x4c
	s_mul_i32 s4, s4, s6
	s_add_i32 s4, s4, s5
	s_mul_hi_i32 s5, s4, 0x6bca1af3
	s_lshr_b32 s6, s5, 31
	s_ashr_i32 s5, s5, 6
	s_add_i32 s5, s5, s6
	s_lshl_b32 s6, s5, 3
	s_mulk_i32 s5, 0x98
	s_sub_i32 s4, s4, s5
	s_sext_i32_i16 s5, s4
	s_bfe_u32 s5, s5, 0x3001c
	s_add_i32 s5, s4, s5
	s_sext_i32_i16 s7, s5
	s_and_b32 s5, s5, 0xfff8
	s_sub_i32 s4, s4, s5
	s_sext_i32_i16 s4, s4
	s_add_i32 s28, s6, s4
	s_ashr_i32 s30, s7, 3

; template <bool COOP>
; __global__ void __launch_bounds__(NTHREADS, 2) mega(Params p0) {
;     ...
;                 if (G == 256 && lt.bid >= 96 && !(ph0 & 1)) { __syncthreads(); convert_layer(p, lt, l, 864, CONV_TILES, lt.bid - 96, 160, (float*)lds); } }
.LBB0_434:
	s_cmpk_lt_i32 s86, 0x60
	v_readlane_b32 s4, v253, 21
	s_cselect_b64 s[0:1], -1, 0
	v_readlane_b32 s5, v253, 22
	s_or_b64 s[0:1], s[4:5], s[0:1]
	s_and_b64 vcc, exec, s[0:1]
	s_cbranch_vccnz .LBB0_464
	s_branch .LBB0_464
